# v17: v15 + sample attention selected branch: V rows staged HBM->LDS by LDS-DMA issued together with the K row loads (one round trip instead of three), straight-line exponentials with pipelined bias lo
# speedup vs baseline: 1.0075x; 1.0075x over previous
.LBB0_1868:
	v_add_u32_e32 v0, s30, v4
	v_add_u32_e32 v0, v0, v3
	v_lshrrev_b32_e32 v0, 1, v0
	s_waitcnt vmcnt(0) lgkmcnt(0)
	s_barrier
	v_and_b32_e32 v121, 0xfe, v0
	v_readlane_b32 s8, v238, 3
	s_xor_b32 s21, s30, 3
	v_add_u32_e32 v171, 8, v157
	v_cmp_ge_u32_e32 vcc, s8, v121
	s_and_b64 vcc, exec, vcc
	v_add_u32_e32 v170, 9, v157
	v_add_u32_e32 v169, 10, v157
	v_add_u32_e32 v168, 11, v157
	v_add_u32_e32 v167, 24, v157
	v_add_u32_e32 v166, 25, v157
	v_add_u32_e32 v165, 26, v157
	v_add_u32_e32 v164, 27, v157
	v_mov_b32_e32 v14, 0
	v_mov_b32_e32 v13, 0
	v_mov_b32_e32 v12, 0
	v_mov_b32_e32 v11, 0
	v_mov_b32_e32 v10, 0
	v_mov_b32_e32 v9, 0
	v_mov_b32_e32 v8, 0
	v_mov_b32_e32 v7, 0
	v_mov_b32_e32 v6, 0
	v_mov_b32_e32 v5, 0
	v_mov_b32_e32 v4, 0
	v_mov_b32_e32 v3, 0
	v_mov_b32_e32 v2, 0
	v_mov_b32_e32 v1, 0
	v_mov_b32_e32 v0, 0
	v_mov_b32_e32 v31, 0
	v_mov_b32_e32 v30, 0
	v_mov_b32_e32 v29, 0
	v_mov_b32_e32 v28, 0
	v_mov_b32_e32 v27, 0
	v_mov_b32_e32 v26, 0
	v_mov_b32_e32 v25, 0
	v_mov_b32_e32 v24, 0
	v_mov_b32_e32 v23, 0
	v_mov_b32_e32 v22, 0
	v_mov_b32_e32 v21, 0
	v_mov_b32_e32 v20, 0
	v_mov_b32_e32 v19, 0
	v_mov_b32_e32 v18, 0
	v_mov_b32_e32 v17, 0
	v_mov_b32_e32 v16, 0
	v_mov_b32_e32 v47, 0
	v_mov_b32_e32 v46, 0
	v_mov_b32_e32 v45, 0
	v_mov_b32_e32 v44, 0
	v_mov_b32_e32 v43, 0
	v_mov_b32_e32 v42, 0
	v_mov_b32_e32 v41, 0
	v_mov_b32_e32 v40, 0
	v_mov_b32_e32 v39, 0
	v_mov_b32_e32 v38, 0
	v_mov_b32_e32 v37, 0
	v_mov_b32_e32 v36, 0
	v_mov_b32_e32 v35, 0
	v_mov_b32_e32 v34, 0
	v_mov_b32_e32 v33, 0
	v_mov_b32_e32 v32, 0
	v_mov_b32_e32 v63, 0
	v_mov_b32_e32 v62, 0
	v_mov_b32_e32 v61, 0
	v_mov_b32_e32 v60, 0
	v_mov_b32_e32 v59, 0
	v_mov_b32_e32 v58, 0
	v_mov_b32_e32 v57, 0
	v_mov_b32_e32 v56, 0
	v_mov_b32_e32 v55, 0
	v_mov_b32_e32 v54, 0
	v_mov_b32_e32 v53, 0
	v_mov_b32_e32 v52, 0
	v_mov_b32_e32 v51, 0
	v_mov_b32_e32 v50, 0
	v_mov_b32_e32 v49, 0
	v_mov_b32_e32 v48, 0
	v_mov_b32_e32 v120, 0
	s_cbranch_vccnz .LBB0_1913
	s_lshl_b64 s[8:9], s[22:23], 14
	s_add_u32 s2, s2, s8
	s_addc_u32 s3, s3, s9
	s_add_u32 s2, s2, s20
	v_readlane_b32 s36, v239, 3
	s_addc_u32 s3, s3, 0
	s_lshl_b32 s33, s28, 5
	v_readlane_b32 s46, v239, 13
	v_readlane_b32 s47, v239, 14
	s_add_u32 s12, s46, s20
	v_readlane_b32 s37, v239, 4
	s_addc_u32 s13, s47, 0
	s_bitcmp1_b32 s87, 6
	v_readlane_b32 s37, v238, 3
	s_cselect_b64 s[26:27], -1, 0
	s_lshl_b32 s10, s37, 5
	s_and_b32 s34, s10, 32
	s_lshl_b32 s10, s37, 3
	s_and_b32 s10, s10, 0x1ffffff0
	s_lshl_b32 s11, s21, 2
	s_or_b32 s10, s10, s11
	v_and_b32_e32 v0, 1, v64
	s_add_i32 s10, s10, 0
	v_mov_b32_e32 v117, 0
	v_or_b32_e32 v122, 0x2000, v149
	s_mov_b64 s[64:65], s[56:57]
	s_mov_b64 s[76:77], s[68:69]
	v_cmp_eq_u32_e64 s[8:9], 1, v0
	v_or_b32_e32 v123, 0x1ff8, v149
	v_or_b32_e32 v124, 0x1ff0, v149
	v_or_b32_e32 v125, 0x1fe8, v149
	s_add_i32 s35, s10, 0x27180
	s_movk_i32 s36, 0x80
	v_mov_b32_e32 v120, 0
	v_mov_b32_e32 v0, v117
	v_mov_b32_e32 v1, v117
	v_mov_b32_e32 v2, v117
	v_mov_b32_e32 v3, v117
	v_mov_b32_e32 v4, v117
	v_mov_b32_e32 v5, v117
	v_mov_b32_e32 v6, v117
	v_mov_b32_e32 v7, v117
	v_mov_b32_e32 v8, v117
	v_mov_b32_e32 v9, v117
	v_mov_b32_e32 v10, v117
	v_mov_b32_e32 v11, v117
	v_mov_b32_e32 v12, v117
	v_mov_b32_e32 v13, v117
	v_mov_b32_e32 v14, v117
	v_mov_b32_e32 v15, v117
	v_mov_b32_e32 v16, v117
	v_mov_b32_e32 v17, v117
	v_mov_b32_e32 v18, v117
	v_mov_b32_e32 v19, v117
	v_mov_b32_e32 v20, v117
	v_mov_b32_e32 v21, v117
	v_mov_b32_e32 v22, v117
	v_mov_b32_e32 v23, v117
	v_mov_b32_e32 v24, v117
	v_mov_b32_e32 v25, v117
	v_mov_b32_e32 v26, v117
	v_mov_b32_e32 v27, v117
	v_mov_b32_e32 v28, v117
	v_mov_b32_e32 v29, v117
	v_mov_b32_e32 v30, v117
	v_mov_b32_e32 v31, v117
	v_mov_b32_e32 v32, v117
	v_mov_b32_e32 v33, v117
	v_mov_b32_e32 v34, v117
	v_mov_b32_e32 v35, v117
	v_mov_b32_e32 v36, v117
	v_mov_b32_e32 v37, v117
	v_mov_b32_e32 v38, v117
	v_mov_b32_e32 v39, v117
	v_mov_b32_e32 v40, v117
	v_mov_b32_e32 v41, v117
	v_mov_b32_e32 v42, v117
	v_mov_b32_e32 v43, v117
	v_mov_b32_e32 v44, v117
	v_mov_b32_e32 v45, v117
	v_mov_b32_e32 v46, v117
	v_mov_b32_e32 v47, v117
	v_mov_b32_e32 v48, v117
	v_mov_b32_e32 v49, v117
	v_mov_b32_e32 v50, v117
	v_mov_b32_e32 v51, v117
	v_mov_b32_e32 v52, v117
	v_mov_b32_e32 v53, v117
	v_mov_b32_e32 v54, v117
	v_mov_b32_e32 v55, v117
	v_mov_b32_e32 v56, v117
	v_mov_b32_e32 v57, v117
	v_mov_b32_e32 v58, v117
	v_mov_b32_e32 v59, v117
	v_mov_b32_e32 v60, v117
	v_mov_b32_e32 v61, v117
	v_mov_b32_e32 v62, v117
	v_mov_b32_e32 v63, v117
	v_readlane_b32 s38, v239, 5
	v_readlane_b32 s39, v239, 6
	v_readlane_b32 s40, v239, 7
	v_readlane_b32 s41, v239, 8
	v_readlane_b32 s42, v239, 9
	v_readlane_b32 s43, v239, 10
	v_readlane_b32 s44, v239, 11
	v_readlane_b32 s45, v239, 12
	v_readlane_b32 s48, v239, 15
	v_readlane_b32 s49, v239, 16
	v_readlane_b32 s50, v239, 17
	v_readlane_b32 s51, v239, 18
	s_branch .LBB0_1872
.LBB0_1871:
	s_add_i32 s37, s37, 8
	v_cmp_ge_u32_e32 vcc, s37, v121
	s_add_i32 s35, s35, 64
	s_cbranch_vccnz .LBB0_1913

.LBB0_1878:
	v_min_i32_e32 v64, s38, v150
	v_lshlrev_b32_e32 v116, 11, v64
	v_lshl_add_u64 v[64:65], v[118:119], 0, v[116:117]
	v_lshl_add_u64 v[72:73], v[144:145], 2, v[64:65]
	global_load_dwordx4 v[64:67], v[72:73], off
	global_load_dwordx4 v[68:71], v[72:73], off offset:16
	global_load_dwordx4 v[126:129], v[72:73], off offset:64
	global_load_dwordx4 v[130:133], v[72:73], off offset:80
	global_load_dwordx4 v[134:137], v[72:73], off offset:128
	global_load_dwordx4 v[138:141], v[72:73], off offset:144
	global_load_dwordx4 v[172:175], v[72:73], off offset:192
	global_load_dwordx4 v[176:179], v[72:73], off offset:208
	global_load_dwordx4 v[180:183], v[72:73], off offset:256
	global_load_dwordx4 v[184:187], v[72:73], off offset:272
	global_load_dwordx4 v[188:191], v[72:73], off offset:320
	global_load_dwordx4 v[192:195], v[72:73], off offset:336
	global_load_dwordx4 v[196:199], v[72:73], off offset:384
	global_load_dwordx4 v[200:203], v[72:73], off offset:400
	global_load_dwordx4 v[204:207], v[72:73], off offset:448
	global_load_dwordx4 v[208:211], v[72:73], off offset:464
	v_lshlrev_b32_e32 v116, 2, v163
	v_add_u32_e32 v116, 0x400, v116
	v_lshl_add_u64 v[78:79], v[118:119], 0, v[116:117]
	v_mov_b32_e32 v231, 0
	s_lshl_b32 m0, s87, 8
	v_min_i32_e32 v230, s38, v157
	v_lshlrev_b32_e32 v230, 11, v230
	v_lshl_add_u64 v[232:233], v[78:79], 0, v[230:231]
	global_load_lds_dwordx4 v[232:233], off
	s_add_u32 m0, m0, 0x400
	v_min_i32_e32 v230, s38, v159
	v_lshlrev_b32_e32 v230, 11, v230
	v_lshl_add_u64 v[232:233], v[78:79], 0, v[230:231]
	global_load_lds_dwordx4 v[232:233], off
	s_add_u32 m0, m0, 0x400
	v_min_i32_e32 v230, s38, v158
	v_lshlrev_b32_e32 v230, 11, v230
	v_lshl_add_u64 v[232:233], v[78:79], 0, v[230:231]
	global_load_lds_dwordx4 v[232:233], off
	s_add_u32 m0, m0, 0x400
	v_min_i32_e32 v230, s38, v156
	v_lshlrev_b32_e32 v230, 11, v230
	v_lshl_add_u64 v[232:233], v[78:79], 0, v[230:231]
	global_load_lds_dwordx4 v[232:233], off
	s_add_u32 m0, m0, 0x400
	v_min_i32_e32 v230, s38, v171
	v_lshlrev_b32_e32 v230, 11, v230
	v_lshl_add_u64 v[232:233], v[78:79], 0, v[230:231]
	global_load_lds_dwordx4 v[232:233], off
	s_add_u32 m0, m0, 0x400
	v_min_i32_e32 v230, s38, v170
	v_lshlrev_b32_e32 v230, 11, v230
	v_lshl_add_u64 v[232:233], v[78:79], 0, v[230:231]
	global_load_lds_dwordx4 v[232:233], off
	s_add_u32 m0, m0, 0x400
	v_min_i32_e32 v230, s38, v169
	v_lshlrev_b32_e32 v230, 11, v230
	v_lshl_add_u64 v[232:233], v[78:79], 0, v[230:231]
	global_load_lds_dwordx4 v[232:233], off
	s_add_u32 m0, m0, 0x400
	v_min_i32_e32 v230, s38, v168
	v_lshlrev_b32_e32 v230, 11, v230
	v_lshl_add_u64 v[232:233], v[78:79], 0, v[230:231]
	global_load_lds_dwordx4 v[232:233], off
	s_add_u32 m0, m0, 0x400
	v_min_i32_e32 v230, s38, v155
	v_lshlrev_b32_e32 v230, 11, v230
	v_lshl_add_u64 v[232:233], v[78:79], 0, v[230:231]
	global_load_lds_dwordx4 v[232:233], off
	s_add_u32 m0, m0, 0x400
	v_min_i32_e32 v230, s38, v154
	v_lshlrev_b32_e32 v230, 11, v230
	v_lshl_add_u64 v[232:233], v[78:79], 0, v[230:231]
	global_load_lds_dwordx4 v[232:233], off
	s_add_u32 m0, m0, 0x400
	v_min_i32_e32 v230, s38, v153
	v_lshlrev_b32_e32 v230, 11, v230
	v_lshl_add_u64 v[232:233], v[78:79], 0, v[230:231]
	global_load_lds_dwordx4 v[232:233], off
	s_add_u32 m0, m0, 0x400
	v_min_i32_e32 v230, s38, v152
	v_lshlrev_b32_e32 v230, 11, v230
	v_lshl_add_u64 v[232:233], v[78:79], 0, v[230:231]
	global_load_lds_dwordx4 v[232:233], off
	s_add_u32 m0, m0, 0x400
	v_min_i32_e32 v230, s38, v167
	v_lshlrev_b32_e32 v230, 11, v230
	v_lshl_add_u64 v[232:233], v[78:79], 0, v[230:231]
	global_load_lds_dwordx4 v[232:233], off
	s_add_u32 m0, m0, 0x400
	v_min_i32_e32 v230, s38, v166
	v_lshlrev_b32_e32 v230, 11, v230
	v_lshl_add_u64 v[232:233], v[78:79], 0, v[230:231]
	global_load_lds_dwordx4 v[232:233], off
	s_add_u32 m0, m0, 0x400
	v_min_i32_e32 v230, s38, v165
	v_lshlrev_b32_e32 v230, 11, v230
	v_lshl_add_u64 v[232:233], v[78:79], 0, v[230:231]
	global_load_lds_dwordx4 v[232:233], off
	s_add_u32 m0, m0, 0x400
	v_min_i32_e32 v230, s38, v164
	v_lshlrev_b32_e32 v230, 11, v230
	v_lshl_add_u64 v[232:233], v[78:79], 0, v[230:231]
	global_load_lds_dwordx4 v[232:233], off
	v_mbcnt_hi_u32_b32 v234, -1, v216
	s_lshl_b32 s30, s87, 8
	v_lshl_add_u32 v234, v234, 4, s30
	s_or_b32 s30, s39, s34
	v_add_u32_e32 v116, s30, v157
	s_waitcnt vmcnt(16)
	v_cvt_pk_bf16_f32 v64, v64, v65
	v_cvt_pk_bf16_f32 v65, v66, v67
	v_cvt_pk_bf16_f32 v66, v68, v69
	v_cvt_pk_bf16_f32 v67, v70, v71
	v_cvt_pk_bf16_f32 v126, v126, v127
	v_cvt_pk_bf16_f32 v127, v128, v129
	v_mfma_f32_32x32x16_bf16 v[64:79], v[64:67], v[80:83], 0
	v_cvt_pk_bf16_f32 v128, v130, v131
	v_cvt_pk_bf16_f32 v129, v132, v133
	v_cvt_pk_bf16_f32 v130, v134, v135
	v_cvt_pk_bf16_f32 v131, v136, v137
	v_cvt_pk_bf16_f32 v132, v138, v139
	v_cvt_pk_bf16_f32 v133, v140, v141
	v_mfma_f32_32x32x16_bf16 v[64:79], v[126:129], v[84:87], v[64:79]
	v_cvt_pk_bf16_f32 v126, v172, v173
	v_cvt_pk_bf16_f32 v127, v174, v175
	v_cvt_pk_bf16_f32 v128, v176, v177
	v_cvt_pk_bf16_f32 v129, v178, v179
	v_mfma_f32_32x32x16_bf16 v[64:79], v[130:133], v[88:91], v[64:79]
	v_cvt_pk_bf16_f32 v130, v180, v181
	v_cvt_pk_bf16_f32 v131, v182, v183
	v_cvt_pk_bf16_f32 v132, v184, v185
	v_cvt_pk_bf16_f32 v133, v186, v187
	v_mfma_f32_32x32x16_bf16 v[64:79], v[126:129], v[92:95], v[64:79]
	v_cvt_pk_bf16_f32 v126, v188, v189
	v_cvt_pk_bf16_f32 v127, v190, v191
	v_cvt_pk_bf16_f32 v128, v192, v193
	v_cvt_pk_bf16_f32 v129, v194, v195
	v_mfma_f32_32x32x16_bf16 v[64:79], v[130:133], v[96:99], v[64:79]
	v_cvt_pk_bf16_f32 v130, v196, v197
	v_cvt_pk_bf16_f32 v131, v198, v199
	v_cvt_pk_bf16_f32 v132, v200, v201
	v_cvt_pk_bf16_f32 v133, v202, v203
	v_mfma_f32_32x32x16_bf16 v[64:79], v[126:129], v[100:103], v[64:79]
	v_cvt_pk_bf16_f32 v126, v204, v205
	v_cvt_pk_bf16_f32 v127, v206, v207
	v_cvt_pk_bf16_f32 v128, v208, v209
	v_cvt_pk_bf16_f32 v129, v210, v211
	v_mfma_f32_32x32x16_bf16 v[64:79], v[130:133], v[104:107], v[64:79]
	s_nop 0
	v_mfma_f32_32x32x16_bf16 v[64:79], v[126:129], v[108:111], v[64:79]
	v_add_u32_e32 v189, 1, v116
	v_add_u32_e32 v190, 2, v116
	v_add_u32_e32 v191, 3, v116
	v_sub_u32_e32 v192, v122, v116
	v_min_u32_e32 v192, 0x80, v192
	v_lshl_add_u32 v192, v192, 2, v151
	ds_read_b32 v172, v192
	v_sub_u32_e32 v193, v122, v189
	v_min_u32_e32 v193, 0x80, v193
	v_lshl_add_u32 v193, v193, 2, v151
	ds_read_b32 v173, v193
	v_sub_u32_e32 v194, v122, v190
	v_min_u32_e32 v194, 0x80, v194
	v_lshl_add_u32 v194, v194, 2, v151
	ds_read_b32 v174, v194
	v_sub_u32_e32 v195, v122, v191
	v_min_u32_e32 v195, 0x80, v195
	v_lshl_add_u32 v195, v195, 2, v151
	ds_read_b32 v175, v195
	v_sub_u32_e32 v192, v123, v116
	v_min_u32_e32 v192, 0x80, v192
	v_lshl_add_u32 v192, v192, 2, v151
	ds_read_b32 v176, v192
	v_sub_u32_e32 v193, v123, v189
	v_min_u32_e32 v193, 0x80, v193
	v_lshl_add_u32 v193, v193, 2, v151
	ds_read_b32 v177, v193
	v_sub_u32_e32 v194, v123, v190
	v_min_u32_e32 v194, 0x80, v194
	v_lshl_add_u32 v194, v194, 2, v151
	ds_read_b32 v178, v194
	v_sub_u32_e32 v195, v123, v191
	v_min_u32_e32 v195, 0x80, v195
	v_lshl_add_u32 v195, v195, 2, v151
	ds_read_b32 v179, v195
	v_sub_u32_e32 v192, v124, v116
	v_min_u32_e32 v192, 0x80, v192
	v_lshl_add_u32 v192, v192, 2, v151
	ds_read_b32 v180, v192
	v_sub_u32_e32 v193, v124, v189
	v_min_u32_e32 v193, 0x80, v193
	v_lshl_add_u32 v193, v193, 2, v151
	ds_read_b32 v181, v193
	v_sub_u32_e32 v194, v124, v190
	v_min_u32_e32 v194, 0x80, v194
	v_lshl_add_u32 v194, v194, 2, v151
	ds_read_b32 v182, v194
	v_sub_u32_e32 v195, v124, v191
	v_min_u32_e32 v195, 0x80, v195
	v_lshl_add_u32 v195, v195, 2, v151
	ds_read_b32 v183, v195
	s_waitcnt lgkmcnt(11)
	v_add_f32_e32 v196, v64, v172
	v_exp_f32_e32 v196, v196
	v_sub_u32_e32 v235, v122, v116
	v_cmp_lt_i32_e32 vcc, -1, v235
	s_and_b64 vcc, vcc, s[28:29]
	v_cndmask_b32_e32 v196, 0, v196, vcc
	v_add_f32_e32 v236, 0, v196
	v_sub_u32_e32 v192, v125, v116
	v_min_u32_e32 v192, 0x80, v192
	v_lshl_add_u32 v192, v192, 2, v151
	ds_read_b32 v184, v192
	s_waitcnt lgkmcnt(11)
	v_add_f32_e32 v197, v65, v173
	v_exp_f32_e32 v197, v197
	v_sub_u32_e32 v235, v122, v189
	v_cmp_lt_i32_e32 vcc, -1, v235
	s_and_b64 vcc, vcc, s[28:29]
	v_cndmask_b32_e32 v197, 0, v197, vcc
	v_add_f32_e32 v236, v236, v197
	v_sub_u32_e32 v193, v125, v189
	v_min_u32_e32 v193, 0x80, v193
	v_lshl_add_u32 v193, v193, 2, v151
	ds_read_b32 v185, v193
	s_waitcnt lgkmcnt(11)
	v_add_f32_e32 v198, v66, v174
	v_exp_f32_e32 v198, v198
	v_sub_u32_e32 v235, v122, v190
	v_cmp_lt_i32_e32 vcc, -1, v235
	s_and_b64 vcc, vcc, s[28:29]
	v_cndmask_b32_e32 v198, 0, v198, vcc
	v_add_f32_e32 v236, v236, v198
	v_sub_u32_e32 v194, v125, v190
	v_min_u32_e32 v194, 0x80, v194
	v_lshl_add_u32 v194, v194, 2, v151
	ds_read_b32 v186, v194
	s_waitcnt lgkmcnt(11)
	v_add_f32_e32 v199, v67, v175
	v_exp_f32_e32 v199, v199
	v_sub_u32_e32 v235, v122, v191
	v_cmp_lt_i32_e32 vcc, -1, v235
	s_and_b64 vcc, vcc, s[28:29]
	v_cndmask_b32_e32 v199, 0, v199, vcc
	v_add_f32_e32 v236, v236, v199
	v_sub_u32_e32 v195, v125, v191
	v_min_u32_e32 v195, 0x80, v195
	v_lshl_add_u32 v195, v195, 2, v151
	ds_read_b32 v187, v195
	s_waitcnt lgkmcnt(11)
	v_add_f32_e32 v200, v68, v176
	v_exp_f32_e32 v200, v200
	v_sub_u32_e32 v235, v123, v116
	v_cmp_lt_i32_e32 vcc, -1, v235
	s_and_b64 vcc, vcc, s[28:29]
	v_cndmask_b32_e32 v200, 0, v200, vcc
	v_add_f32_e32 v236, v236, v200
	s_waitcnt lgkmcnt(10)
	v_add_f32_e32 v201, v69, v177
	v_exp_f32_e32 v201, v201
	v_sub_u32_e32 v235, v123, v189
	v_cmp_lt_i32_e32 vcc, -1, v235
	s_and_b64 vcc, vcc, s[28:29]
	v_cndmask_b32_e32 v201, 0, v201, vcc
	v_add_f32_e32 v236, v236, v201
	s_waitcnt lgkmcnt(9)
	v_add_f32_e32 v202, v70, v178
	v_exp_f32_e32 v202, v202
	v_sub_u32_e32 v235, v123, v190
	v_cmp_lt_i32_e32 vcc, -1, v235
	s_and_b64 vcc, vcc, s[28:29]
	v_cndmask_b32_e32 v202, 0, v202, vcc
	v_add_f32_e32 v236, v236, v202
	s_waitcnt lgkmcnt(8)
	v_add_f32_e32 v203, v71, v179
	v_exp_f32_e32 v203, v203
	v_sub_u32_e32 v235, v123, v191
	v_cmp_lt_i32_e32 vcc, -1, v235
	s_and_b64 vcc, vcc, s[28:29]
	v_cndmask_b32_e32 v203, 0, v203, vcc
	v_add_f32_e32 v236, v236, v203
	s_waitcnt lgkmcnt(7)
	v_add_f32_e32 v204, v72, v180
	v_exp_f32_e32 v204, v204
	v_sub_u32_e32 v235, v124, v116
	v_cmp_lt_i32_e32 vcc, -1, v235
	s_and_b64 vcc, vcc, s[28:29]
	v_cndmask_b32_e32 v204, 0, v204, vcc
	v_add_f32_e32 v236, v236, v204
	s_waitcnt lgkmcnt(6)
	v_add_f32_e32 v205, v73, v181
	v_exp_f32_e32 v205, v205
	v_sub_u32_e32 v235, v124, v189
	v_cmp_lt_i32_e32 vcc, -1, v235
	s_and_b64 vcc, vcc, s[28:29]
	v_cndmask_b32_e32 v205, 0, v205, vcc
	v_add_f32_e32 v236, v236, v205
	s_waitcnt lgkmcnt(5)
	v_add_f32_e32 v206, v74, v182
	v_exp_f32_e32 v206, v206
	v_sub_u32_e32 v235, v124, v190
	v_cmp_lt_i32_e32 vcc, -1, v235
	s_and_b64 vcc, vcc, s[28:29]
	v_cndmask_b32_e32 v206, 0, v206, vcc
	v_add_f32_e32 v236, v236, v206
	s_waitcnt lgkmcnt(4)
	v_add_f32_e32 v207, v75, v183
	v_exp_f32_e32 v207, v207
	v_sub_u32_e32 v235, v124, v191
	v_cmp_lt_i32_e32 vcc, -1, v235
	s_and_b64 vcc, vcc, s[28:29]
	v_cndmask_b32_e32 v207, 0, v207, vcc
	v_add_f32_e32 v236, v236, v207
	s_waitcnt lgkmcnt(3)
	v_add_f32_e32 v208, v76, v184
	v_exp_f32_e32 v208, v208
	v_sub_u32_e32 v235, v125, v116
	v_cmp_lt_i32_e32 vcc, -1, v235
	s_and_b64 vcc, vcc, s[28:29]
	v_cndmask_b32_e32 v208, 0, v208, vcc
	v_add_f32_e32 v236, v236, v208
	s_waitcnt lgkmcnt(2)
	v_add_f32_e32 v209, v77, v185
	v_exp_f32_e32 v209, v209
	v_sub_u32_e32 v235, v125, v189
	v_cmp_lt_i32_e32 vcc, -1, v235
	s_and_b64 vcc, vcc, s[28:29]
	v_cndmask_b32_e32 v209, 0, v209, vcc
	v_add_f32_e32 v236, v236, v209
	s_waitcnt lgkmcnt(1)
	v_add_f32_e32 v210, v78, v186
	v_exp_f32_e32 v210, v210
	v_sub_u32_e32 v235, v125, v190
	v_cmp_lt_i32_e32 vcc, -1, v235
	s_and_b64 vcc, vcc, s[28:29]
	v_cndmask_b32_e32 v210, 0, v210, vcc
	v_add_f32_e32 v236, v236, v210
	s_waitcnt lgkmcnt(0)
	v_add_f32_e32 v211, v79, v187
	v_exp_f32_e32 v211, v211
	v_sub_u32_e32 v235, v125, v191
	v_cmp_lt_i32_e32 vcc, -1, v235
	s_and_b64 vcc, vcc, s[28:29]
	v_cndmask_b32_e32 v211, 0, v211, vcc
	v_add_f32_e32 v236, v236, v211
	v_add_f32_e32 v120, v120, v236
	v_cvt_pk_bf16_f32 v64, v196, v197
	v_cvt_pk_bf16_f32 v65, v198, v199
	v_cvt_pk_bf16_f32 v66, v200, v201
	v_cvt_pk_bf16_f32 v67, v202, v203
	v_cvt_pk_bf16_f32 v68, v204, v205
	v_cvt_pk_bf16_f32 v69, v206, v207
	v_cvt_pk_bf16_f32 v70, v208, v209
	v_cvt_pk_bf16_f32 v71, v210, v211
	s_waitcnt vmcnt(0)
	ds_read_b128 v[128:131], v234 offset:0
	ds_read_b128 v[132:135], v234 offset:1024
	ds_read_b128 v[136:139], v234 offset:2048
	ds_read_b128 v[140:143], v234 offset:3072
	ds_read_b128 v[172:175], v234 offset:4096
	ds_read_b128 v[176:179], v234 offset:5120
	ds_read_b128 v[180:183], v234 offset:6144
	ds_read_b128 v[184:187], v234 offset:7168
	ds_read_b128 v[188:191], v234 offset:8192
	ds_read_b128 v[192:195], v234 offset:9216
	ds_read_b128 v[196:199], v234 offset:10240
	ds_read_b128 v[200:203], v234 offset:11264
	s_waitcnt lgkmcnt(4)
	ds_read_b128 v[204:207], v234 offset:12288
	ds_read_b128 v[208:211], v234 offset:13312
	ds_read_b128 v[212:215], v234 offset:14336
	ds_read_b128 v[218:221], v234 offset:15360
	v_cvt_pk_bf16_f32 v222, v128, v132
	v_cvt_pk_bf16_f32 v223, v136, v140
	v_cvt_pk_bf16_f32 v224, v172, v176
	v_cvt_pk_bf16_f32 v225, v180, v184
	s_nop 1
	v_mfma_f32_32x32x16_bf16 v[0:15], v[64:67], v[222:225], v[0:15]
	v_cvt_pk_bf16_f32 v226, v129, v133
	v_cvt_pk_bf16_f32 v227, v137, v141
	v_cvt_pk_bf16_f32 v228, v173, v177
	v_cvt_pk_bf16_f32 v229, v181, v185
	s_nop 1
	v_mfma_f32_32x32x16_bf16 v[16:31], v[64:67], v[226:229], v[16:31]
	v_cvt_pk_bf16_f32 v222, v130, v134
	v_cvt_pk_bf16_f32 v223, v138, v142
	v_cvt_pk_bf16_f32 v224, v174, v178
	v_cvt_pk_bf16_f32 v225, v182, v186
	s_nop 1
	v_mfma_f32_32x32x16_bf16 v[32:47], v[64:67], v[222:225], v[32:47]
	v_cvt_pk_bf16_f32 v226, v131, v135
	v_cvt_pk_bf16_f32 v227, v139, v143
	v_cvt_pk_bf16_f32 v228, v175, v179
	v_cvt_pk_bf16_f32 v229, v183, v187
	s_nop 1
	v_mfma_f32_32x32x16_bf16 v[48:63], v[64:67], v[226:229], v[48:63]
	s_waitcnt lgkmcnt(0)
	v_cvt_pk_bf16_f32 v222, v188, v192
	v_cvt_pk_bf16_f32 v223, v196, v200
	v_cvt_pk_bf16_f32 v224, v204, v208
	v_cvt_pk_bf16_f32 v225, v212, v218
	s_nop 1
	v_mfma_f32_32x32x16_bf16 v[0:15], v[68:71], v[222:225], v[0:15]
	v_cvt_pk_bf16_f32 v226, v189, v193
	v_cvt_pk_bf16_f32 v227, v197, v201
	v_cvt_pk_bf16_f32 v228, v205, v209
	v_cvt_pk_bf16_f32 v229, v213, v219
	s_nop 1
	v_mfma_f32_32x32x16_bf16 v[16:31], v[68:71], v[226:229], v[16:31]
	v_cvt_pk_bf16_f32 v222, v190, v194
	v_cvt_pk_bf16_f32 v223, v198, v202
	v_cvt_pk_bf16_f32 v224, v206, v210
	v_cvt_pk_bf16_f32 v225, v214, v220
	s_nop 1
	v_mfma_f32_32x32x16_bf16 v[32:47], v[68:71], v[222:225], v[32:47]
	v_cvt_pk_bf16_f32 v226, v191, v195
	v_cvt_pk_bf16_f32 v227, v199, v203
	v_cvt_pk_bf16_f32 v228, v207, v211
	v_cvt_pk_bf16_f32 v229, v215, v221
	s_nop 1
	v_mfma_f32_32x32x16_bf16 v[48:63], v[68:71], v[226:229], v[48:63]
	s_branch .LBB0_1871
